# attention item: work-queue next-item atomic claim made asynchronous (result consumed at item end with vmcnt(4)) instead of a synchronous vmcnt(0) wait in wave 0
# baseline (speedup 1.0000x reference)
; #define LAS __attribute__((address_space(3)))
; __device__ __forceinline__ void unpack8(const u32x4 w, float (&f)[8]) { f[0] = bflo(w.x); f[1] = bfhi(w.x); f[2] = bflo(w.y); f[3] = bfhi(w.y); f[4] = bflo(w.z); f[5] = bfhi(w.z); f[6] = bflo(w.w); f[7] = bfhi(w.w); }
; __device__ __forceinline__ void attn_item(const Params& P, int half, int item, LAS unsigned char* lds, unsigned* ctr) {
;     ...
;     {
;         const bf16_t* qp = Z + (size_t)qrow * ZC + colq + 8 * g;
;         qpos = (float)P.pos[gtb + qrow];
; #pragma unroll
;         for (int kh = 0; kh < 2; ++kh) { qx1[kh] = *(const u32x4*)(qp + kh * 32); qx2[kh] = *(const u32x4*)(qp + 64 + kh * 32);
;             qinv[2 * kh] = *(const f32x4*)(RC + kh * 32 + 8 * g); qinv[2 * kh + 1] = *(const f32x4*)(RC + kh * 32 + 8 * g + 4); }
;     }
;     {
;         LAS unsigned char* kd = Ks + km * KSTR;
; #pragma unroll
;         for (int cc = 0; cc < 4; ++cc) {
;             float x1[8], x2[8], o1[8], o2[8];
;             unpack8(kx1[cc], x1); unpack8(kx2[cc], x2);
;             f32x4 c0, c1, s0, s1;
; #pragma unroll
;             for (int j = 0; j < 4; ++j) { const float r0 = __builtin_amdgcn_fractf(kpos * kinv[2 * cc][j]), r1 = __builtin_amdgcn_fractf(kpos * kinv[2 * cc + 1][j]);
;                 c0[j] = __builtin_amdgcn_cosf(r0); s0[j] = __builtin_amdgcn_sinf(r0); c1[j] = __builtin_amdgcn_cosf(r1); s1[j] = __builtin_amdgcn_sinf(r1); }
; #pragma unroll
;             for (int j = 0; j < 4; j += 2) {
;                 { const f32x2 X1 = (f32x2){x1[j], x1[j + 1]}, X2 = (f32x2){x2[j], x2[j + 1]}, C = (f32x2){c0[j], c0[j + 1]}, Sn = (f32x2){s0[j], s0[j + 1]};
;                   const f32x2 A = X1 * C - X2 * Sn, B = X2 * C + X1 * Sn; o1[j] = A.x; o1[j + 1] = A.y; o2[j] = B.x; o2[j + 1] = B.y; }
;                 { const f32x2 X1 = (f32x2){x1[4 + j], x1[5 + j]}, X2 = (f32x2){x2[4 + j], x2[5 + j]}, C = (f32x2){c1[j], c1[j + 1]}, Sn = (f32x2){s1[j], s1[j + 1]};
;                   const f32x2 A = X1 * C - X2 * Sn, B = X2 * C + X1 * Sn; o1[4 + j] = A.x; o1[5 + j] = A.y; o2[4 + j] = B.x; o2[5 + j] = B.y; } }
;             *(LAS u32x4*)(kd + (khf * 32 + cc * 8) * 2) = pack8(o1); *(LAS u32x4*)(kd + (64 + khf * 32 + cc * 8) * 2) = pack8(o2);
;         }
;     }
.LBB0_535:
	s_or_b64 exec, exec, s[30:31]
	s_ashr_i32 s6, s6, 2
	v_bfi_b32 v138, -16, s6, v137
	v_add_u32_e32 v42, s10, v138
	v_lshlrev_b32_e32 v42, s7, v42
	v_add_u32_e32 v133, s11, v42
	v_add_u32_e32 v44, s44, v133
	v_readlane_b32 s48, v252, 9
	v_ashrrev_i32_e32 v45, 31, v44
	v_readlane_b32 s50, v252, 11
	v_readlane_b32 s51, v252, 12
	s_add_i32 s8, s8, s9
	v_mov_b64_e32 v[42:43], s[28:29]
	v_lshl_add_u64 v[44:45], v[44:45], 2, s[50:51]
	global_load_dword v141, v[44:45], off
	v_bfe_u32 v136, v137, 4, 2
	s_add_i32 s20, s8, 0xc00
	v_mad_i64_i32 v[42:43], s[8:9], v133, s25, v[42:43]
	v_lshl_add_u64 v[130:131], s[20:21], 1, v[42:43]
	v_lshlrev_b32_e32 v194, 4, v136
	v_readlane_b32 s8, v251, 35
	v_lshl_add_u64 v[42:43], v[130:131], 0, v[194:195]
	v_lshlrev_b32_e32 v54, 5, v136
	v_readlane_b32 s9, v251, 36
	s_nop 4
	global_load_dwordx4 v[90:93], v54, s[8:9] offset:16
	global_load_dwordx4 v[94:97], v54, s[8:9]
	global_load_dwordx4 v[110:113], v[42:43], off
	global_load_dwordx4 v[78:81], v[42:43], off offset:64
	global_load_dwordx4 v[106:109], v[42:43], off offset:128
	global_load_dwordx4 v[74:77], v[42:43], off offset:192
	s_nop 0
	global_load_dwordx4 v[42:45], v54, s[8:9] offset:144
	s_nop 0
	global_load_dwordx4 v[54:57], v54, s[8:9] offset:128
	s_waitcnt vmcnt(16)
	v_mul_f32_e32 v118, v118, v139
	v_fract_f32_e32 v150, v118
	s_waitcnt vmcnt(15)
	v_mul_f32_e32 v118, v122, v139
	v_fract_f32_e32 v151, v118
	v_mul_f32_e32 v119, v119, v139
	v_cos_f32_e32 v118, v150
	v_sin_f32_e32 v122, v150
	v_cos_f32_e32 v150, v151
	v_sin_f32_e32 v152, v151
	v_fract_f32_e32 v151, v119
	v_mul_f32_e32 v120, v120, v139
	v_mul_f32_e32 v119, v123, v139
	v_sin_f32_e32 v123, v151
	v_fract_f32_e32 v154, v120
	v_mul_f32_e32 v120, v124, v139
	v_fract_f32_e32 v153, v119
	v_cos_f32_e32 v119, v151
	v_fract_f32_e32 v155, v120
	v_mul_f32_e32 v121, v121, v139
	s_movk_i32 s7, 0x110
	v_cos_f32_e32 v151, v153
	v_sin_f32_e32 v153, v153
	v_cos_f32_e32 v120, v154
	v_sin_f32_e32 v124, v154
	v_cos_f32_e32 v154, v155
	v_sin_f32_e32 v156, v155
	v_fract_f32_e32 v155, v121
	v_mul_f32_e32 v121, v125, v139
	v_mul_lo_u32 v142, v142, s7
	v_lshlrev_b32_e32 v146, 16, v114
	v_and_b32_e32 v147, 0xffff0000, v114
	v_fract_f32_e32 v157, v121
	v_cos_f32_e32 v121, v155
	v_sin_f32_e32 v125, v155
	v_add3_u32 v134, 0, v142, v134
	v_lshlrev_b32_e32 v142, 16, v126
	v_and_b32_e32 v143, 0xffff0000, v126
	v_cos_f32_e32 v155, v157
	v_sin_f32_e32 v157, v157
	v_pk_mul_f32 v[158:159], v[122:123], v[146:147]
	v_lshlrev_b32_e32 v148, 16, v116
	v_and_b32_e32 v149, 0xffff0000, v116
	v_pk_fma_f32 v[158:159], v[118:119], v[142:143], v[158:159] neg_lo:[0,0,1] neg_hi:[0,0,1]
	v_pk_mul_f32 v[118:119], v[118:119], v[146:147]
	v_lshlrev_b32_e32 v144, 16, v128
	v_and_b32_e32 v145, 0xffff0000, v128
	v_lshlrev_b32_e32 v114, 16, v115
	v_and_b32_e32 v115, 0xffff0000, v115
	v_pk_fma_f32 v[118:119], v[122:123], v[142:143], v[118:119]
	v_pk_mul_f32 v[122:123], v[152:153], v[148:149]
	v_pk_mul_f32 v[142:143], v[150:151], v[148:149]
	v_lshlrev_b32_e32 v126, 16, v127
	v_and_b32_e32 v127, 0xffff0000, v127
	v_lshlrev_b32_e32 v116, 16, v117
	v_and_b32_e32 v117, 0xffff0000, v117
	v_pk_fma_f32 v[122:123], v[150:151], v[144:145], v[122:123] neg_lo:[0,0,1] neg_hi:[0,0,1]
	v_pk_fma_f32 v[142:143], v[152:153], v[144:145], v[142:143]
	v_pk_mul_f32 v[144:145], v[124:125], v[114:115]
	v_pk_mul_f32 v[114:115], v[120:121], v[114:115]
	v_lshlrev_b32_e32 v128, 16, v129
	v_and_b32_e32 v129, 0xffff0000, v129
	v_pk_fma_f32 v[144:145], v[120:121], v[126:127], v[144:145] neg_lo:[0,0,1] neg_hi:[0,0,1]
	v_pk_fma_f32 v[120:121], v[124:125], v[126:127], v[114:115]
	v_pk_mul_f32 v[114:115], v[156:157], v[116:117]
	s_waitcnt vmcnt(14)
	v_mul_f32_e32 v82, v82, v139
	v_pk_fma_f32 v[124:125], v[154:155], v[128:129], v[114:115] neg_lo:[0,0,1] neg_hi:[0,0,1]
	v_pk_mul_f32 v[114:115], v[154:155], v[116:117]
	v_mul_f32_e32 v83, v83, v139
	v_pk_fma_f32 v[126:127], v[156:157], v[128:129], v[114:115]
	v_cvt_pk_bf16_f32 v114, v158, v159
	v_cvt_pk_bf16_f32 v115, v144, v145
	v_cvt_pk_bf16_f32 v116, v122, v123
	v_fract_f32_e32 v122, v82
	s_waitcnt vmcnt(13)
	v_mul_f32_e32 v82, v86, v139
	v_fract_f32_e32 v123, v82
	v_cvt_pk_bf16_f32 v117, v124, v125
	v_cos_f32_e32 v82, v122
	v_sin_f32_e32 v86, v122
	v_cos_f32_e32 v122, v123
	v_sin_f32_e32 v124, v123
	v_fract_f32_e32 v123, v83
	v_mul_f32_e32 v83, v87, v139
	v_sin_f32_e32 v87, v123
	v_mul_f32_e32 v84, v84, v139
	ds_write_b128 v134, v[114:117]
	v_cvt_pk_bf16_f32 v114, v118, v119
	v_cvt_pk_bf16_f32 v115, v120, v121
	v_cvt_pk_bf16_f32 v116, v142, v143
	v_cvt_pk_bf16_f32 v117, v126, v127
	v_fract_f32_e32 v125, v83
	v_cos_f32_e32 v83, v123
	v_fract_f32_e32 v126, v84
	v_mul_f32_e32 v84, v88, v139
	v_cos_f32_e32 v123, v125
	v_sin_f32_e32 v125, v125
	v_fract_f32_e32 v127, v84
	v_mul_f32_e32 v85, v85, v139
	v_lshlrev_b32_e32 v118, 16, v98
	v_and_b32_e32 v119, 0xffff0000, v98
	v_cos_f32_e32 v84, v126
	v_sin_f32_e32 v88, v126
	v_cos_f32_e32 v126, v127
	v_sin_f32_e32 v128, v127
	v_fract_f32_e32 v127, v85
	ds_write_b128 v134, v[114:117] offset:128
	v_lshlrev_b32_e32 v114, 16, v102
	v_and_b32_e32 v115, 0xffff0000, v102
	v_mul_f32_e32 v85, v89, v139
	v_sin_f32_e32 v89, v127
	v_pk_mul_f32 v[142:143], v[86:87], v[118:119]
	v_lshlrev_b32_e32 v120, 16, v100
	v_and_b32_e32 v121, 0xffff0000, v100
	v_fract_f32_e32 v129, v85
	v_cos_f32_e32 v85, v127
	v_pk_fma_f32 v[142:143], v[82:83], v[114:115], v[142:143] neg_lo:[0,0,1] neg_hi:[0,0,1]
	v_pk_mul_f32 v[82:83], v[82:83], v[118:119]
	v_lshlrev_b32_e32 v116, 16, v104
	v_and_b32_e32 v117, 0xffff0000, v104
	v_cos_f32_e32 v127, v129
	v_sin_f32_e32 v129, v129
	v_pk_fma_f32 v[86:87], v[86:87], v[114:115], v[82:83]
	v_pk_mul_f32 v[82:83], v[124:125], v[120:121]
	v_lshlrev_b32_e32 v98, 16, v99
	v_and_b32_e32 v99, 0xffff0000, v99
	v_pk_fma_f32 v[114:115], v[122:123], v[116:117], v[82:83] neg_lo:[0,0,1] neg_hi:[0,0,1]
	v_pk_mul_f32 v[82:83], v[122:123], v[120:121]
	v_lshlrev_b32_e32 v102, 16, v103
	v_and_b32_e32 v103, 0xffff0000, v103
	v_pk_fma_f32 v[116:117], v[124:125], v[116:117], v[82:83]
	v_pk_mul_f32 v[82:83], v[88:89], v[98:99]
	v_lshlrev_b32_e32 v100, 16, v101
	v_and_b32_e32 v101, 0xffff0000, v101
	v_pk_fma_f32 v[118:119], v[84:85], v[102:103], v[82:83] neg_lo:[0,0,1] neg_hi:[0,0,1]
	v_pk_mul_f32 v[82:83], v[84:85], v[98:99]
	v_lshlrev_b32_e32 v104, 16, v105
	v_and_b32_e32 v105, 0xffff0000, v105
	v_pk_fma_f32 v[88:89], v[88:89], v[102:103], v[82:83]
	v_pk_mul_f32 v[82:83], v[128:129], v[100:101]
	s_waitcnt vmcnt(12)
; #define LAS __attribute__((address_space(3)))
; __device__ __forceinline__ void unpack8(const u32x4 w, float (&f)[8]) { f[0] = bflo(w.x); f[1] = bfhi(w.x); f[2] = bflo(w.y); f[3] = bfhi(w.y); f[4] = bflo(w.z); f[5] = bfhi(w.z); f[6] = bflo(w.w); f[7] = bfhi(w.w); }
; __device__ __forceinline__ u32x4 pack8(const float (&f)[8]) { u32x4 w; w.x = cvt_pk_bf16(f[0], f[1]); w.y = cvt_pk_bf16(f[2], f[3]); w.z = cvt_pk_bf16(f[4], f[5]); w.w = cvt_pk_bf16(f[6], f[7]); return w; }
; __device__ __forceinline__ void attn_item(const Params& P, int half, int item, LAS unsigned char* lds, unsigned* ctr) {
;     ...
; #pragma unroll
;         for (int cc = 0; cc < 4; ++cc) {
;             float x1[8], x2[8], o1[8], o2[8];
;             unpack8(kx1[cc], x1); unpack8(kx2[cc], x2);
;             f32x4 c0, c1, s0, s1;
; #pragma unroll
;             for (int j = 0; j < 4; ++j) { const float r0 = __builtin_amdgcn_fractf(kpos * kinv[2 * cc][j]), r1 = __builtin_amdgcn_fractf(kpos * kinv[2 * cc + 1][j]);
;                 c0[j] = __builtin_amdgcn_cosf(r0); s0[j] = __builtin_amdgcn_sinf(r0); c1[j] = __builtin_amdgcn_cosf(r1); s1[j] = __builtin_amdgcn_sinf(r1); }
; #pragma unroll
;             for (int j = 0; j < 4; j += 2) {
;                 { const f32x2 X1 = (f32x2){x1[j], x1[j + 1]}, X2 = (f32x2){x2[j], x2[j + 1]}, C = (f32x2){c0[j], c0[j + 1]}, Sn = (f32x2){s0[j], s0[j + 1]};
;                   const f32x2 A = X1 * C - X2 * Sn, B = X2 * C + X1 * Sn; o1[j] = A.x; o1[j + 1] = A.y; o2[j] = B.x; o2[j + 1] = B.y; }
;                 { const f32x2 X1 = (f32x2){x1[4 + j], x1[5 + j]}, X2 = (f32x2){x2[4 + j], x2[5 + j]}, C = (f32x2){c1[j], c1[j + 1]}, Sn = (f32x2){s1[j], s1[j + 1]};
;                   const f32x2 A = X1 * C - X2 * Sn, B = X2 * C + X1 * Sn; o1[4 + j] = A.x; o1[5 + j] = A.y; o2[4 + j] = B.x; o2[5 + j] = B.y; } }
;             *(LAS u32x4*)(kd + (khf * 32 + cc * 8) * 2) = pack8(o1); *(LAS u32x4*)(kd + (64 + khf * 32 + cc * 8) * 2) = pack8(o2);
;         }
	v_mul_f32_e32 v38, v38, v139
	v_pk_fma_f32 v[98:99], v[126:127], v[104:105], v[82:83] neg_lo:[0,0,1] neg_hi:[0,0,1]
	v_pk_mul_f32 v[82:83], v[126:127], v[100:101]
	v_mul_f32_e32 v39, v39, v139
	v_pk_fma_f32 v[100:101], v[128:129], v[104:105], v[82:83]
	v_cvt_pk_bf16_f32 v82, v142, v143
	v_cvt_pk_bf16_f32 v83, v118, v119
	v_cvt_pk_bf16_f32 v84, v114, v115
	v_cvt_pk_bf16_f32 v85, v98, v99
	v_fract_f32_e32 v98, v38
	s_waitcnt vmcnt(11)
	v_mul_f32_e32 v38, v46, v139
	v_fract_f32_e32 v99, v38
	ds_write_b128 v134, v[82:85] offset:16
	v_cvt_pk_bf16_f32 v82, v86, v87
	v_cvt_pk_bf16_f32 v83, v88, v89
	v_cvt_pk_bf16_f32 v84, v116, v117
	v_cvt_pk_bf16_f32 v85, v100, v101
	v_cos_f32_e32 v38, v98
	v_sin_f32_e32 v46, v98
	v_cos_f32_e32 v98, v99
	v_sin_f32_e32 v100, v99
	v_fract_f32_e32 v99, v39
	v_mul_f32_e32 v39, v47, v139
	v_sin_f32_e32 v47, v99
	v_mul_f32_e32 v40, v40, v139
	v_fract_f32_e32 v101, v39
	v_cos_f32_e32 v39, v99
	v_fract_f32_e32 v102, v40
	v_mul_f32_e32 v40, v48, v139
	v_cos_f32_e32 v99, v101
	v_sin_f32_e32 v101, v101
	v_fract_f32_e32 v103, v40
	v_mul_f32_e32 v41, v41, v139
	v_lshlrev_b32_e32 v86, 16, v62
	v_and_b32_e32 v87, 0xffff0000, v62
	v_cos_f32_e32 v40, v102
	v_sin_f32_e32 v48, v102
	v_cos_f32_e32 v102, v103
	v_sin_f32_e32 v104, v103
	v_fract_f32_e32 v103, v41
	ds_write_b128 v134, v[82:85] offset:144
	v_lshlrev_b32_e32 v82, 16, v66
	v_and_b32_e32 v83, 0xffff0000, v66
	v_mul_f32_e32 v41, v49, v139
	v_sin_f32_e32 v49, v103
	v_pk_mul_f32 v[114:115], v[46:47], v[86:87]
	v_lshlrev_b32_e32 v88, 16, v64
	v_and_b32_e32 v89, 0xffff0000, v64
	v_fract_f32_e32 v105, v41
	v_cos_f32_e32 v41, v103
	v_pk_fma_f32 v[114:115], v[38:39], v[82:83], v[114:115] neg_lo:[0,0,1] neg_hi:[0,0,1]
	v_pk_mul_f32 v[38:39], v[38:39], v[86:87]
	v_lshlrev_b32_e32 v84, 16, v68
	v_and_b32_e32 v85, 0xffff0000, v68
	v_cos_f32_e32 v103, v105
	v_sin_f32_e32 v105, v105
	v_pk_fma_f32 v[46:47], v[46:47], v[82:83], v[38:39]
	v_pk_mul_f32 v[38:39], v[100:101], v[88:89]
	v_lshlrev_b32_e32 v62, 16, v63
	v_and_b32_e32 v63, 0xffff0000, v63
	v_pk_fma_f32 v[82:83], v[98:99], v[84:85], v[38:39] neg_lo:[0,0,1] neg_hi:[0,0,1]
	v_pk_mul_f32 v[38:39], v[98:99], v[88:89]
	v_lshlrev_b32_e32 v66, 16, v67
	v_and_b32_e32 v67, 0xffff0000, v67
	v_pk_fma_f32 v[84:85], v[100:101], v[84:85], v[38:39]
	v_pk_mul_f32 v[38:39], v[48:49], v[62:63]
	v_lshlrev_b32_e32 v64, 16, v65
	v_and_b32_e32 v65, 0xffff0000, v65
	v_pk_fma_f32 v[86:87], v[40:41], v[66:67], v[38:39] neg_lo:[0,0,1] neg_hi:[0,0,1]
	v_pk_mul_f32 v[38:39], v[40:41], v[62:63]
	v_lshlrev_b32_e32 v68, 16, v69
	v_and_b32_e32 v69, 0xffff0000, v69
	v_pk_fma_f32 v[48:49], v[48:49], v[66:67], v[38:39]
	v_pk_mul_f32 v[38:39], v[104:105], v[64:65]
	s_waitcnt vmcnt(10)
	v_mul_f32_e32 v2, v2, v139
	v_pk_fma_f32 v[62:63], v[102:103], v[68:69], v[38:39] neg_lo:[0,0,1] neg_hi:[0,0,1]
	v_pk_mul_f32 v[38:39], v[102:103], v[64:65]
	v_mul_f32_e32 v3, v3, v139
	v_pk_fma_f32 v[64:65], v[104:105], v[68:69], v[38:39]
	v_cvt_pk_bf16_f32 v38, v114, v115
	v_cvt_pk_bf16_f32 v39, v86, v87
	v_cvt_pk_bf16_f32 v40, v82, v83
	v_cvt_pk_bf16_f32 v41, v62, v63
	v_fract_f32_e32 v62, v2
	s_waitcnt vmcnt(9)
	v_mul_f32_e32 v2, v10, v139
	v_fract_f32_e32 v63, v2
	ds_write_b128 v134, v[38:41] offset:32
	v_cvt_pk_bf16_f32 v38, v46, v47
	v_cvt_pk_bf16_f32 v39, v48, v49
	v_cvt_pk_bf16_f32 v40, v84, v85
	v_cvt_pk_bf16_f32 v41, v64, v65
	v_cos_f32_e32 v2, v62
	v_sin_f32_e32 v10, v62
	v_cos_f32_e32 v62, v63
	v_sin_f32_e32 v64, v63
	v_fract_f32_e32 v63, v3
	v_mul_f32_e32 v3, v11, v139
	v_sin_f32_e32 v11, v63
	v_mul_f32_e32 v4, v4, v139
	v_fract_f32_e32 v65, v3
	v_cos_f32_e32 v3, v63
	v_fract_f32_e32 v66, v4
	v_mul_f32_e32 v4, v12, v139
	v_cos_f32_e32 v63, v65
	v_sin_f32_e32 v65, v65
	v_fract_f32_e32 v67, v4
	v_mul_f32_e32 v5, v5, v139
	v_lshlrev_b32_e32 v46, 16, v6
	v_and_b32_e32 v47, 0xffff0000, v6
	v_cos_f32_e32 v4, v66
	v_sin_f32_e32 v12, v66
	v_cos_f32_e32 v66, v67
	v_sin_f32_e32 v68, v67
	v_fract_f32_e32 v67, v5
	ds_write_b128 v134, v[38:41] offset:160
	v_lshlrev_b32_e32 v38, 16, v14
	v_and_b32_e32 v39, 0xffff0000, v14
	v_mul_f32_e32 v5, v13, v139
	v_sin_f32_e32 v13, v67
	v_pk_mul_f32 v[82:83], v[10:11], v[46:47]
	v_lshlrev_b32_e32 v48, 16, v8
	v_and_b32_e32 v49, 0xffff0000, v8
	v_fract_f32_e32 v69, v5
	v_cos_f32_e32 v5, v67
	v_pk_fma_f32 v[82:83], v[2:3], v[38:39], v[82:83] neg_lo:[0,0,1] neg_hi:[0,0,1]
	v_pk_mul_f32 v[2:3], v[2:3], v[46:47]
	v_lshlrev_b32_e32 v40, 16, v16
	v_and_b32_e32 v41, 0xffff0000, v16
	v_cos_f32_e32 v67, v69
	v_sin_f32_e32 v69, v69
	v_pk_fma_f32 v[10:11], v[10:11], v[38:39], v[2:3]
	v_pk_mul_f32 v[2:3], v[64:65], v[48:49]
	v_lshlrev_b32_e32 v6, 16, v7
	v_and_b32_e32 v7, 0xffff0000, v7
	v_pk_fma_f32 v[38:39], v[62:63], v[40:41], v[2:3] neg_lo:[0,0,1] neg_hi:[0,0,1]
	v_pk_mul_f32 v[2:3], v[62:63], v[48:49]
	v_lshlrev_b32_e32 v14, 16, v15
	v_and_b32_e32 v15, 0xffff0000, v15
	v_pk_fma_f32 v[40:41], v[64:65], v[40:41], v[2:3]
	v_pk_mul_f32 v[2:3], v[12:13], v[6:7]
	v_lshlrev_b32_e32 v8, 16, v9
	v_and_b32_e32 v9, 0xffff0000, v9
	v_pk_fma_f32 v[46:47], v[4:5], v[14:15], v[2:3] neg_lo:[0,0,1] neg_hi:[0,0,1]
	v_pk_mul_f32 v[2:3], v[4:5], v[6:7]
	v_lshlrev_b32_e32 v16, 16, v17
	v_and_b32_e32 v17, 0xffff0000, v17
	v_pk_fma_f32 v[6:7], v[12:13], v[14:15], v[2:3]
	v_pk_mul_f32 v[2:3], v[68:69], v[8:9]
	s_movk_i32 s7, 0x210
	v_pk_fma_f32 v[12:13], v[66:67], v[16:17], v[2:3] neg_lo:[0,0,1] neg_hi:[0,0,1]
	v_pk_mul_f32 v[2:3], v[66:67], v[8:9]
	s_mov_b32 s8, 0x3e0293ee
	v_pk_fma_f32 v[8:9], v[68:69], v[16:17], v[2:3]
	v_cvt_pk_bf16_f32 v2, v82, v83
	v_cvt_pk_bf16_f32 v3, v46, v47
	v_cvt_pk_bf16_f32 v4, v38, v39
	v_cvt_pk_bf16_f32 v5, v12, v13
	ds_write_b128 v134, v[2:5] offset:48
; #define LAS __attribute__((address_space(3)))
; __device__ __forceinline__ void attn_item(const Params& P, int half, int item, LAS unsigned char* lds, unsigned* ctr) {
;     ...
;     {
; #pragma unroll
;         for (int dd = 0; dd < 8; ++dd) {
;             const int wi = dd >> 1; u32x4 o;
;             if (dd & 1) { o.x = __builtin_amdgcn_perm(rv[1][wi], rv[0][wi], 0x07060302u); o.y = __builtin_amdgcn_perm(rv[3][wi], rv[2][wi], 0x07060302u); o.z = __builtin_amdgcn_perm(rv[5][wi], rv[4][wi], 0x07060302u); o.w = __builtin_amdgcn_perm(rv[7][wi], rv[6][wi], 0x07060302u); }
;             else { o.x = __builtin_amdgcn_perm(rv[1][wi], rv[0][wi], 0x05040100u); o.y = __builtin_amdgcn_perm(rv[3][wi], rv[2][wi], 0x05040100u); o.z = __builtin_amdgcn_perm(rv[5][wi], rv[4][wi], 0x05040100u); o.w = __builtin_amdgcn_perm(rv[7][wi], rv[6][wi], 0x05040100u); }
;             *(LAS u32x4*)(Vt + (vdb * 8 + dd) * VSTR + vkb * 16) = o;
;         }
;     }
;     bf16x8 Qf[4];
;     {
; #pragma unroll
;         for (int kh = 0; kh < 2; ++kh) {
;             float x1[8], x2[8], o1[8], o2[8];
;             unpack8(qx1[kh], x1); unpack8(qx2[kh], x2);
;             f32x4 c0, c1, s0, s1;
; #pragma unroll
;             for (int j = 0; j < 4; ++j) { const float r0 = __builtin_amdgcn_fractf(qpos * qinv[2 * kh][j]), r1 = __builtin_amdgcn_fractf(qpos * qinv[2 * kh + 1][j]);
;                 c0[j] = __builtin_amdgcn_cosf(r0); s0[j] = __builtin_amdgcn_sinf(r0); c1[j] = __builtin_amdgcn_cosf(r1); s1[j] = __builtin_amdgcn_sinf(r1); }
; #pragma unroll
;             for (int j = 0; j < 4; j += 2) {
;                 { const f32x2 X1 = (f32x2){x1[j], x1[j + 1]} * QSCALE, X2 = (f32x2){x2[j], x2[j + 1]} * QSCALE, C = (f32x2){c0[j], c0[j + 1]}, Sn = (f32x2){s0[j], s0[j + 1]};
;                   const f32x2 A = X1 * C - X2 * Sn, B = X2 * C + X1 * Sn; o1[j] = A.x; o1[j + 1] = A.y; o2[j] = B.x; o2[j + 1] = B.y; }
;                 { const f32x2 X1 = (f32x2){x1[4 + j], x1[5 + j]} * QSCALE, X2 = (f32x2){x2[4 + j], x2[5 + j]} * QSCALE, C = (f32x2){c1[j], c1[j + 1]}, Sn = (f32x2){s1[j], s1[j + 1]};
;                   const f32x2 A = X1 * C - X2 * Sn, B = X2 * C + X1 * Sn; o1[4 + j] = A.x; o1[5 + j] = A.y; o2[4 + j] = B.x; o2[5 + j] = B.y; } }
;             Qf[kh] = as_bf16x8(pack8(o1)); Qf[kh + 2] = as_bf16x8(pack8(o2));
	v_cvt_pk_bf16_f32 v2, v10, v11
	v_cvt_pk_bf16_f32 v3, v6, v7
	v_cvt_pk_bf16_f32 v4, v40, v41
	v_cvt_pk_bf16_f32 v5, v8, v9
	v_lshlrev_b32_e32 v6, 4, v140
	v_mul_lo_u32 v7, v132, s7
	v_readlane_b32 s7, v255, 16
	ds_write_b128 v134, v[2:5] offset:176
	v_perm_b32 v2, v22, v18, s92
	v_perm_b32 v3, v30, v26, s92
	v_perm_b32 v4, v58, v50, s92
	v_perm_b32 v5, v34, v70, s92
	v_add3_u32 v6, s7, v6, v7
	s_mov_b32 s7, 0x7060302
	ds_write_b128 v6, v[2:5]
	v_perm_b32 v2, v22, v18, s7
	v_perm_b32 v3, v30, v26, s7
	v_perm_b32 v4, v58, v50, s7
	v_perm_b32 v5, v34, v70, s7
	ds_write_b128 v6, v[2:5] offset:528
	v_perm_b32 v2, v23, v19, s92
	v_perm_b32 v3, v31, v27, s92
	v_perm_b32 v4, v59, v51, s92
	v_perm_b32 v5, v35, v71, s92
	ds_write_b128 v6, v[2:5] offset:1056
	v_perm_b32 v2, v23, v19, s7
	v_perm_b32 v3, v31, v27, s7
	v_perm_b32 v4, v59, v51, s7
	v_perm_b32 v5, v35, v71, s7
	ds_write_b128 v6, v[2:5] offset:1584
	v_perm_b32 v2, v24, v20, s92
	v_perm_b32 v3, v32, v28, s92
	v_perm_b32 v4, v60, v52, s92
	v_perm_b32 v5, v36, v72, s92
	ds_write_b128 v6, v[2:5] offset:2112
	v_perm_b32 v2, v24, v20, s7
	v_perm_b32 v3, v32, v28, s7
	v_perm_b32 v4, v60, v52, s7
	v_perm_b32 v5, v36, v72, s7
	ds_write_b128 v6, v[2:5] offset:2640
	v_perm_b32 v2, v25, v21, s92
	v_perm_b32 v3, v33, v29, s92
	v_perm_b32 v4, v61, v53, s92
	v_perm_b32 v5, v37, v73, s92
	ds_write_b128 v6, v[2:5] offset:3168
	v_perm_b32 v5, v37, v73, s7
	s_waitcnt vmcnt(8)
	v_cvt_f32_i32_e32 v37, v141
	v_perm_b32 v2, v25, v21, s7
	v_perm_b32 v3, v33, v29, s7
	v_perm_b32 v4, v61, v53, s7
	s_waitcnt vmcnt(6)
	v_mul_f32_e32 v18, v94, v37
	v_fract_f32_e32 v19, v18
	v_mul_f32_e32 v18, v90, v37
	v_fract_f32_e32 v21, v18
	v_cos_f32_e32 v18, v19
	v_sin_f32_e32 v20, v19
	v_mul_f32_e32 v19, v95, v37
	v_cos_f32_e32 v22, v21
	v_sin_f32_e32 v24, v21
	v_fract_f32_e32 v21, v19
	v_mul_f32_e32 v19, v91, v37
	v_fract_f32_e32 v25, v19
	v_cos_f32_e32 v19, v21
	v_sin_f32_e32 v21, v21
	v_mul_f32_e32 v26, v96, v37
	v_fract_f32_e32 v27, v26
	v_mul_f32_e32 v26, v92, v37
	s_waitcnt vmcnt(3)
	v_lshlrev_b32_e32 v10, 16, v106
	v_and_b32_e32 v11, 0xffff0000, v106
	v_cos_f32_e32 v23, v25
	v_sin_f32_e32 v25, v25
	v_fract_f32_e32 v29, v26
	v_cos_f32_e32 v26, v27
	v_sin_f32_e32 v28, v27
	v_mul_f32_e32 v27, v97, v37
	ds_write_b128 v6, v[2:5] offset:3696
	v_lshlrev_b32_e32 v2, 16, v110
	v_and_b32_e32 v3, 0xffff0000, v110
	v_cos_f32_e32 v30, v29
	v_sin_f32_e32 v32, v29
	v_fract_f32_e32 v29, v27
	v_mul_f32_e32 v27, v93, v37
	v_pk_mul_f32 v[10:11], v[10:11], s[8:9] op_sel_hi:[1,0]
	v_lshlrev_b32_e32 v14, 16, v108
	v_and_b32_e32 v15, 0xffff0000, v108
	v_fract_f32_e32 v33, v27
	v_cos_f32_e32 v27, v29
	v_sin_f32_e32 v29, v29
	v_pk_mul_f32 v[2:3], v[2:3], s[8:9] op_sel_hi:[1,0]
	v_pk_mul_f32 v[34:35], v[10:11], v[20:21]
	v_pk_mul_f32 v[10:11], v[10:11], v[18:19]
	v_lshlrev_b32_e32 v6, 16, v112
	v_and_b32_e32 v7, 0xffff0000, v112
	v_pk_fma_f32 v[34:35], v[2:3], v[18:19], v[34:35] neg_lo:[0,0,1] neg_hi:[0,0,1]
	v_pk_fma_f32 v[2:3], v[2:3], v[20:21], v[10:11]
	v_pk_mul_f32 v[10:11], v[14:15], s[8:9] op_sel_hi:[1,0]
	v_lshlrev_b32_e32 v12, 16, v107
	v_and_b32_e32 v13, 0xffff0000, v107
	v_pk_mul_f32 v[6:7], v[6:7], s[8:9] op_sel_hi:[1,0]
	v_pk_mul_f32 v[14:15], v[10:11], v[24:25]
	v_pk_mul_f32 v[10:11], v[10:11], v[22:23]
	v_lshlrev_b32_e32 v4, 16, v111
	v_and_b32_e32 v5, 0xffff0000, v111
	v_cos_f32_e32 v31, v33
	v_sin_f32_e32 v33, v33
	v_pk_fma_f32 v[14:15], v[6:7], v[22:23], v[14:15] neg_lo:[0,0,1] neg_hi:[0,0,1]
	v_pk_fma_f32 v[10:11], v[6:7], v[24:25], v[10:11]
	v_pk_mul_f32 v[6:7], v[12:13], s[8:9] op_sel_hi:[1,0]
	v_pk_mul_f32 v[4:5], v[4:5], s[8:9] op_sel_hi:[1,0]
	v_pk_mul_f32 v[12:13], v[6:7], v[28:29]
	v_lshlrev_b32_e32 v8, 16, v113
	v_and_b32_e32 v9, 0xffff0000, v113
	v_lshlrev_b32_e32 v16, 16, v109
	v_and_b32_e32 v17, 0xffff0000, v109
	v_pk_fma_f32 v[12:13], v[4:5], v[26:27], v[12:13] neg_lo:[0,0,1] neg_hi:[0,0,1]
	v_pk_mul_f32 v[6:7], v[6:7], v[26:27]
	s_waitcnt vmcnt(0)
; __device__ __forceinline__ void unpack8(const u32x4 w, float (&f)[8]) { f[0] = bflo(w.x); f[1] = bfhi(w.x); f[2] = bflo(w.y); f[3] = bfhi(w.y); f[4] = bflo(w.z); f[5] = bfhi(w.z); f[6] = bflo(w.w); f[7] = bfhi(w.w); }
; __device__ __forceinline__ u32x4 pack8(const float (&f)[8]) { u32x4 w; w.x = cvt_pk_bf16(f[0], f[1]); w.y = cvt_pk_bf16(f[2], f[3]); w.z = cvt_pk_bf16(f[4], f[5]); w.w = cvt_pk_bf16(f[6], f[7]); return w; }
; __device__ __forceinline__ void attn_item(const Params& P, int half, int item, LAS unsigned char* lds, unsigned* ctr) {
;     ...
;     bf16x8 Qf[4];
;     {
; #pragma unroll
;         for (int kh = 0; kh < 2; ++kh) {
;             float x1[8], x2[8], o1[8], o2[8];
;             unpack8(qx1[kh], x1); unpack8(qx2[kh], x2);
;             f32x4 c0, c1, s0, s1;
; #pragma unroll
;             for (int j = 0; j < 4; ++j) { const float r0 = __builtin_amdgcn_fractf(qpos * qinv[2 * kh][j]), r1 = __builtin_amdgcn_fractf(qpos * qinv[2 * kh + 1][j]);
;                 c0[j] = __builtin_amdgcn_cosf(r0); s0[j] = __builtin_amdgcn_sinf(r0); c1[j] = __builtin_amdgcn_cosf(r1); s1[j] = __builtin_amdgcn_sinf(r1); }
; #pragma unroll
;             for (int j = 0; j < 4; j += 2) {
;                 { const f32x2 X1 = (f32x2){x1[j], x1[j + 1]} * QSCALE, X2 = (f32x2){x2[j], x2[j + 1]} * QSCALE, C = (f32x2){c0[j], c0[j + 1]}, Sn = (f32x2){s0[j], s0[j + 1]};
;                   const f32x2 A = X1 * C - X2 * Sn, B = X2 * C + X1 * Sn; o1[j] = A.x; o1[j + 1] = A.y; o2[j] = B.x; o2[j + 1] = B.y; }
;                 { const f32x2 X1 = (f32x2){x1[4 + j], x1[5 + j]} * QSCALE, X2 = (f32x2){x2[4 + j], x2[5 + j]} * QSCALE, C = (f32x2){c1[j], c1[j + 1]}, Sn = (f32x2){s1[j], s1[j + 1]};
;                   const f32x2 A = X1 * C - X2 * Sn, B = X2 * C + X1 * Sn; o1[4 + j] = A.x; o1[5 + j] = A.y; o2[4 + j] = B.x; o2[5 + j] = B.y; } }
;             Qf[kh] = as_bf16x8(pack8(o1)); Qf[kh + 2] = as_bf16x8(pack8(o2));
;         }
;     }
;     __syncthreads();
;     unsigned nxt_id = 0u;
;     if (tid == 0) nxt_id = atomicAdd(ctr, 1u);
	v_mul_f32_e32 v26, v54, v37
	v_pk_fma_f32 v[4:5], v[4:5], v[28:29], v[6:7]
	v_pk_mul_f32 v[6:7], v[8:9], s[8:9] op_sel_hi:[1,0]
	v_pk_mul_f32 v[8:9], v[16:17], s[8:9] op_sel_hi:[1,0]
	v_fract_f32_e32 v27, v26
	v_mul_f32_e32 v26, v42, v37
	v_pk_mul_f32 v[16:17], v[8:9], v[32:33]
	v_pk_mul_f32 v[8:9], v[8:9], v[30:31]
	v_fract_f32_e32 v29, v26
	v_cos_f32_e32 v26, v27
	v_sin_f32_e32 v28, v27
	v_mul_f32_e32 v27, v55, v37
	v_pk_fma_f32 v[16:17], v[6:7], v[30:31], v[16:17] neg_lo:[0,0,1] neg_hi:[0,0,1]
	v_pk_fma_f32 v[18:19], v[6:7], v[32:33], v[8:9]
	v_cos_f32_e32 v30, v29
	v_sin_f32_e32 v32, v29
	v_fract_f32_e32 v29, v27
	v_mul_f32_e32 v27, v43, v37
	v_cvt_pk_bf16_f32 v6, v34, v35
	v_fract_f32_e32 v33, v27
	v_cos_f32_e32 v27, v29
	v_sin_f32_e32 v29, v29
	v_mul_f32_e32 v34, v56, v37
	v_fract_f32_e32 v35, v34
	v_mul_f32_e32 v34, v44, v37
	v_cvt_pk_bf16_f32 v7, v12, v13
	v_cvt_pk_bf16_f32 v8, v14, v15
	v_cvt_pk_bf16_f32 v9, v16, v17
	v_cvt_pk_bf16_f32 v2, v2, v3
	v_cvt_pk_bf16_f32 v3, v4, v5
	v_cvt_pk_bf16_f32 v4, v10, v11
	v_cvt_pk_bf16_f32 v5, v18, v19
	v_lshlrev_b32_e32 v18, 16, v74
	v_and_b32_e32 v19, 0xffff0000, v74
	v_cos_f32_e32 v31, v33
	v_sin_f32_e32 v33, v33
	v_fract_f32_e32 v39, v34
	v_cos_f32_e32 v34, v35
	v_sin_f32_e32 v36, v35
	v_mul_f32_e32 v35, v57, v37
	v_lshlrev_b32_e32 v10, 16, v78
	v_and_b32_e32 v11, 0xffff0000, v78
	v_cos_f32_e32 v38, v39
	v_sin_f32_e32 v40, v39
	v_fract_f32_e32 v39, v35
	v_mul_f32_e32 v35, v45, v37
	v_pk_mul_f32 v[18:19], v[18:19], s[8:9] op_sel_hi:[1,0]
	v_lshlrev_b32_e32 v22, 16, v76
	v_and_b32_e32 v23, 0xffff0000, v76
	v_fract_f32_e32 v41, v35
	v_cos_f32_e32 v35, v39
	v_sin_f32_e32 v37, v39
	v_pk_mul_f32 v[10:11], v[10:11], s[8:9] op_sel_hi:[1,0]
	v_pk_mul_f32 v[42:43], v[18:19], v[28:29]
	v_pk_mul_f32 v[18:19], v[18:19], v[26:27]
	v_lshlrev_b32_e32 v14, 16, v80
	v_and_b32_e32 v15, 0xffff0000, v80
	v_pk_fma_f32 v[42:43], v[10:11], v[26:27], v[42:43] neg_lo:[0,0,1] neg_hi:[0,0,1]
	v_pk_fma_f32 v[10:11], v[10:11], v[28:29], v[18:19]
	v_pk_mul_f32 v[18:19], v[22:23], s[8:9] op_sel_hi:[1,0]
	v_lshlrev_b32_e32 v20, 16, v75
	v_and_b32_e32 v21, 0xffff0000, v75
	v_cos_f32_e32 v39, v41
	v_sin_f32_e32 v41, v41
	v_pk_mul_f32 v[14:15], v[14:15], s[8:9] op_sel_hi:[1,0]
	v_pk_mul_f32 v[22:23], v[18:19], v[32:33]
	v_pk_mul_f32 v[18:19], v[18:19], v[30:31]
	v_lshlrev_b32_e32 v12, 16, v79
	v_and_b32_e32 v13, 0xffff0000, v79
	v_pk_fma_f32 v[22:23], v[14:15], v[30:31], v[22:23] neg_lo:[0,0,1] neg_hi:[0,0,1]
	v_pk_fma_f32 v[18:19], v[14:15], v[32:33], v[18:19]
	v_pk_mul_f32 v[14:15], v[20:21], s[8:9] op_sel_hi:[1,0]
	v_lshlrev_b32_e32 v16, 16, v81
	v_and_b32_e32 v17, 0xffff0000, v81
	v_lshlrev_b32_e32 v24, 16, v77
	v_and_b32_e32 v25, 0xffff0000, v77
	v_pk_mul_f32 v[12:13], v[12:13], s[8:9] op_sel_hi:[1,0]
	v_pk_mul_f32 v[20:21], v[14:15], v[36:37]
	v_pk_mul_f32 v[14:15], v[14:15], v[34:35]
	v_pk_fma_f32 v[20:21], v[12:13], v[34:35], v[20:21] neg_lo:[0,0,1] neg_hi:[0,0,1]
	v_pk_fma_f32 v[12:13], v[12:13], v[36:37], v[14:15]
	v_pk_mul_f32 v[14:15], v[16:17], s[8:9] op_sel_hi:[1,0]
	v_pk_mul_f32 v[16:17], v[24:25], s[8:9] op_sel_hi:[1,0]
	v_cmp_eq_u32_e64 s[36:37], 0, v137
	v_pk_mul_f32 v[24:25], v[16:17], v[40:41]
	v_pk_mul_f32 v[16:17], v[16:17], v[38:39]
	v_readlane_b32 s49, v252, 10
	v_readlane_b32 s52, v252, 13
	v_readlane_b32 s53, v252, 14
	v_readlane_b32 s54, v252, 15
	v_readlane_b32 s55, v252, 16
	v_readlane_b32 s56, v252, 17
	v_readlane_b32 s57, v252, 18
	v_readlane_b32 s58, v252, 19
	v_readlane_b32 s59, v252, 20
	v_readlane_b32 s60, v252, 21
	v_readlane_b32 s61, v252, 22
	v_readlane_b32 s62, v252, 23
	v_readlane_b32 s63, v252, 24
	v_pk_fma_f32 v[24:25], v[14:15], v[38:39], v[24:25] neg_lo:[0,0,1] neg_hi:[0,0,1]
	v_pk_fma_f32 v[26:27], v[14:15], v[40:41], v[16:17]
	v_cvt_pk_bf16_f32 v14, v42, v43
	v_cvt_pk_bf16_f32 v15, v20, v21
	v_cvt_pk_bf16_f32 v16, v22, v23
	v_cvt_pk_bf16_f32 v17, v24, v25
	v_cvt_pk_bf16_f32 v10, v10, v11
	v_cvt_pk_bf16_f32 v11, v12, v13
	v_cvt_pk_bf16_f32 v12, v18, v19
	s_nop 0
	v_cvt_pk_bf16_f32 v13, v26, v27
	s_waitcnt lgkmcnt(0)
	s_barrier
	s_and_saveexec_b64 s[30:31], s[36:37]
	s_cbranch_execz .LBB0_539
	v_mov_b32_e32 v135, 1
	global_atomic_add v135, v195, v135, s[0:1] sc0

; #define LAS __attribute__((address_space(3)))
; __device__ __forceinline__ void attn_item(const Params& P, int half, int item, LAS unsigned char* lds, unsigned* ctr) {
;     ...
;     if (g == 0) LSE[(size_t)qrow * 12 + gi * 4 + hh] = (mx + __builtin_amdgcn_logf(den)) * 0.6931471805599453f;
;     if (tid == 0) *(LAS unsigned*)(lds + LDS_SLOT) = nxt_id;
;     __syncthreads();
.LBB0_541:
	s_or_b64 exec, exec, s[30:31]
	s_and_saveexec_b64 s[30:31], s[36:37]
	s_cbranch_execz .LBB0_516
	v_readlane_b32 s2, v255, 15
	s_nop 1
	v_mov_b32_e32 v2, s2
	s_waitcnt vmcnt(4)
	ds_write_b32 v2, v135
	s_branch .LBB0_516
